# GEMM FFN-up/down: last 2 LDS-DMA issues of SP2 load segments moved into the following MFMA segment (vmcnt 8->6)
# speedup vs baseline: 1.0010x; 1.0010x over previous
; #define PG8_STAGE(bufoff, gbase, voff) do { _Pragma("unroll") for (int _i = 0; _i < 2; ++_i) \
;         __builtin_amdgcn_global_load_lds((const unsigned*)((const char*)(gbase) + (voff)[_i]), (PG8_LAS unsigned*)(lds + (bufoff) + ldsw + _i * 8192), 16, 0, 0); } while (0)
; #define PG8_LDA(dst, b, h) do { _Pragma("unroll") for (int m = 0; m < 4; ++m) _Pragma("unroll") for (int k = 0; k < 2; ++k) dst[m][k] = *(const PG8_LAS bf16x8*)(lds + PG8_SA(b, h) + aoff + m * 2048 + k * 1024); } while (0)
; #define PG8_LDB(dst, b, h) do { _Pragma("unroll") for (int n = 0; n < 2; ++n) _Pragma("unroll") for (int k = 0; k < 2; ++k) dst[n][k] = *(const PG8_LAS bf16x8*)(lds + PG8_SB(b, h) + boff + n * 2048 + k * 1024); } while (0)
; #define PG8_MMA(ai, bj, At, Bt) do { __builtin_amdgcn_s_setprio(1); _Pragma("unroll") for (int m = 0; m < 4; ++m) _Pragma("unroll") for (int n = 0; n < 2; ++n) _Pragma("unroll") for (int k = 0; k < 2; ++k) \
;         acc[ai][bj][m][n] = __builtin_amdgcn_mfma_f32_16x16x32_bf16(Bt[n][k], At[m][k], acc[ai][bj][m][n], 0, 0, 0); __builtin_amdgcn_s_setprio(0); } while (0)
; #define PG8_WAIT_V(n) asm volatile("s_waitcnt vmcnt(" #n ")" ::: "memory")
; #define PG8_WAIT_L(n) asm volatile("s_waitcnt lgkmcnt(" #n ")" ::: "memory")
; #define PG8_BAR __builtin_amdgcn_s_barrier()
; #define PG8_SCHED __builtin_amdgcn_sched_barrier(0)
; template <class Epi, class Sched, bool ALIGN_EPI = false, bool SP2 = false>
; __device__ __forceinline__ void gemm_phase(PG8_LAS unsigned char* lds, const Gemm g, const Sched& S, const Epi& E) {
;     ...
;             const bool last = (t == nt - 2);
;             const char* a1 = cA + (size_t)(t + 1) * kstep;
;             const char* a2 = last ? nA : cA + (size_t)(t + 2) * kstep; const char* b2 = last ? nB : cB + (size_t)(t + 2) * kstep;
;             const char* a3 = a2 + kstep; const char* b3 = b2 + kstep;
;             if (last && has_next) S.a_ready(nxt);
;             if constexpr (SP2) {
;             PG8_LDB(B0, 0, 0); PG8_LDB(B1, 0, 1); PG8_SCHED; PG8_LDA(At, 0, 0); PG8_STAGE(PG8_SA(1, 1), a1 + hstepA, voffA);
;             PG8_WAIT_V(8); PG8_WAIT_L(0); PG8_BAR; PG8_MMA(0, 0, At, B0); PG8_MMA(0, 1, At, B1); PG8_BAR; PG8_SCHED;
;             PG8_LDA(At, 0, 1); PG8_STAGE(PG8_SB(0, 0), b2, voffB); PG8_STAGE(PG8_SB(0, 1), b2 + hstepB, voffB); PG8_STAGE(PG8_SA(0, 0), a2, voffA);
.LBB0_297:
	s_add_u32 s2, s8, 0xffe00080
	s_addc_u32 s10, s9, -1
	s_add_i32 s33, s17, 0x100
	s_cmpk_eq_i32 vcc_lo, 0x7c
	s_cselect_b32 s61, s49, s10
	s_cselect_b32 s60, s70, s2
	v_add_u32_e32 v144, s33, v147
	s_cselect_b32 s11, s47, s93
	s_cselect_b32 s10, s74, s91
	s_add_i32 s2, s24, 0x100
	ds_read_b128 v[136:139], v144
	ds_read_b128 v[140:143], v144 offset:1024
	ds_read_b128 v[150:153], v144 offset:2048
	ds_read_b128 v[154:157], v144 offset:3072
	v_add_u32_e32 v144, s2, v147
	ds_read_b128 v[158:161], v144
	ds_read_b128 v[162:165], v144 offset:1024
	ds_read_b128 v[166:169], v144 offset:2048
	ds_read_b128 v[170:173], v144 offset:3072
	v_lshl_add_u64 v[144:145], s[8:9], 0, v[132:133]
	s_add_i32 m0, s63, 0xc000
	ds_read_b128 v[174:177], v149
	ds_read_b128 v[178:181], v149 offset:1024
	ds_read_b128 v[182:185], v149 offset:2048
	ds_read_b128 v[186:189], v149 offset:3072
	ds_read_b128 v[190:193], v149 offset:4096
	ds_read_b128 v[210:213], v149 offset:5120
	ds_read_b128 v[222:225], v149 offset:6144
	ds_read_b128 v[228:231], v149 offset:7168
	global_load_lds_dwordx4 v[144:145], off
	v_lshl_add_u64 v[144:145], s[8:9], 0, v[134:135]
	s_add_i32 m0, s63, 0xe000
	s_nop 0
	global_load_lds_dwordx4 v[144:145], off
	s_waitcnt vmcnt(8)
	s_waitcnt lgkmcnt(0)
	s_barrier
	s_setprio 1
	s_waitcnt lgkmcnt(0)
	v_mfma_f32_16x16x32_bf16 v[126:129], v[136:139], v[174:177], v[126:129]
	v_mfma_f32_16x16x32_bf16 v[122:125], v[150:153], v[174:177], v[122:125]
	v_mfma_f32_16x16x32_bf16 v[110:113], v[136:139], v[182:185], v[110:113]
	v_mfma_f32_16x16x32_bf16 v[106:109], v[150:153], v[182:185], v[106:109]
	v_mfma_f32_16x16x32_bf16 v[94:97], v[136:139], v[190:193], v[94:97]
	v_mfma_f32_16x16x32_bf16 v[90:93], v[150:153], v[190:193], v[90:93]
	v_mfma_f32_16x16x32_bf16 v[78:81], v[136:139], v[222:225], v[78:81]
	v_mfma_f32_16x16x32_bf16 v[74:77], v[150:153], v[222:225], v[74:77]
	v_mfma_f32_16x16x32_bf16 v[126:129], v[140:143], v[178:181], v[126:129]
	v_mfma_f32_16x16x32_bf16 v[122:125], v[154:157], v[178:181], v[122:125]
	v_mfma_f32_16x16x32_bf16 v[110:113], v[140:143], v[186:189], v[110:113]
	v_mfma_f32_16x16x32_bf16 v[106:109], v[154:157], v[186:189], v[106:109]
	v_mfma_f32_16x16x32_bf16 v[94:97], v[140:143], v[210:213], v[94:97]
	v_mfma_f32_16x16x32_bf16 v[90:93], v[154:157], v[210:213], v[90:93]
	v_mfma_f32_16x16x32_bf16 v[78:81], v[140:143], v[228:231], v[78:81]
	v_mfma_f32_16x16x32_bf16 v[74:77], v[154:157], v[228:231], v[74:77]
	s_setprio 0
	s_setprio 1
	v_mfma_f32_16x16x32_bf16 v[118:121], v[158:161], v[174:177], v[118:121]
	v_mfma_f32_16x16x32_bf16 v[114:117], v[166:169], v[174:177], v[114:117]
	v_mfma_f32_16x16x32_bf16 v[102:105], v[158:161], v[182:185], v[102:105]
	v_mfma_f32_16x16x32_bf16 v[98:101], v[166:169], v[182:185], v[98:101]
	v_mfma_f32_16x16x32_bf16 v[86:89], v[158:161], v[190:193], v[86:89]
	v_mfma_f32_16x16x32_bf16 v[82:85], v[166:169], v[190:193], v[82:85]
	v_mfma_f32_16x16x32_bf16 v[70:73], v[158:161], v[222:225], v[70:73]
	v_mfma_f32_16x16x32_bf16 v[66:69], v[166:169], v[222:225], v[66:69]
	v_mfma_f32_16x16x32_bf16 v[118:121], v[162:165], v[178:181], v[118:121]
	v_mfma_f32_16x16x32_bf16 v[114:117], v[170:173], v[178:181], v[114:117]
	v_mfma_f32_16x16x32_bf16 v[102:105], v[162:165], v[186:189], v[102:105]
	v_mfma_f32_16x16x32_bf16 v[98:101], v[170:173], v[186:189], v[98:101]
	v_mfma_f32_16x16x32_bf16 v[86:89], v[162:165], v[210:213], v[86:89]
	v_mfma_f32_16x16x32_bf16 v[82:85], v[170:173], v[210:213], v[82:85]
	v_mfma_f32_16x16x32_bf16 v[70:73], v[162:165], v[228:231], v[70:73]
	v_mfma_f32_16x16x32_bf16 v[66:69], v[170:173], v[228:231], v[66:69]
	s_setprio 0
	s_barrier
	s_add_i32 s33, s33, s36
	v_lshl_add_u64 v[144:145], s[10:11], 0, v[0:1]
	s_mov_b32 m0, s33
	ds_read_b128 v[174:177], v149 offset:16384
	ds_read_b128 v[178:181], v149 offset:17408
	ds_read_b128 v[182:185], v149 offset:18432
	ds_read_b128 v[186:189], v149 offset:19456
	ds_read_b128 v[190:193], v149 offset:20480
	ds_read_b128 v[210:213], v149 offset:21504
	ds_read_b128 v[222:225], v149 offset:22528
	ds_read_b128 v[228:231], v149 offset:23552
	global_load_lds_dwordx4 v[144:145], off
	s_add_i32 m0, s33, 0x2000
	s_add_u32 s78, s10, 0x200000
	v_lshl_add_u64 v[194:195], s[10:11], 0, v[130:131]
	s_addc_u32 s79, s11, 0
	s_add_i32 s2, s2, s36
	global_load_lds_dwordx4 v[194:195], off
	v_lshl_add_u64 v[214:215], s[78:79], 0, v[0:1]
	s_mov_b32 m0, s2
	v_lshl_add_u64 v[232:233], s[60:61], 0, v[130:131]
	global_load_lds_dwordx4 v[214:215], off
	v_lshl_add_u64 v[214:215], s[78:79], 0, v[130:131]
	s_add_i32 m0, s2, 0x2000
	s_nop 0
	global_load_lds_dwordx4 v[214:215], off
	v_lshl_add_u64 v[214:215], s[60:61], 0, v[0:1]
	s_waitcnt vmcnt(6)
	s_waitcnt lgkmcnt(0)
	s_barrier
; #define PG8_STAGE(bufoff, gbase, voff) do { _Pragma("unroll") for (int _i = 0; _i < 2; ++_i) \
;         __builtin_amdgcn_global_load_lds((const unsigned*)((const char*)(gbase) + (voff)[_i]), (PG8_LAS unsigned*)(lds + (bufoff) + ldsw + _i * 8192), 16, 0, 0); } while (0)
; #define PG8_LDA(dst, b, h) do { _Pragma("unroll") for (int m = 0; m < 4; ++m) _Pragma("unroll") for (int k = 0; k < 2; ++k) dst[m][k] = *(const PG8_LAS bf16x8*)(lds + PG8_SA(b, h) + aoff + m * 2048 + k * 1024); } while (0)
; #define PG8_LDB(dst, b, h) do { _Pragma("unroll") for (int n = 0; n < 2; ++n) _Pragma("unroll") for (int k = 0; k < 2; ++k) dst[n][k] = *(const PG8_LAS bf16x8*)(lds + PG8_SB(b, h) + boff + n * 2048 + k * 1024); } while (0)
; #define PG8_MMA(ai, bj, At, Bt) do { __builtin_amdgcn_s_setprio(1); _Pragma("unroll") for (int m = 0; m < 4; ++m) _Pragma("unroll") for (int n = 0; n < 2; ++n) _Pragma("unroll") for (int k = 0; k < 2; ++k) \
;         acc[ai][bj][m][n] = __builtin_amdgcn_mfma_f32_16x16x32_bf16(Bt[n][k], At[m][k], acc[ai][bj][m][n], 0, 0, 0); __builtin_amdgcn_s_setprio(0); } while (0)
; #define PG8_WAIT_V(n) asm volatile("s_waitcnt vmcnt(" #n ")" ::: "memory")
; #define PG8_WAIT_L(n) asm volatile("s_waitcnt lgkmcnt(" #n ")" ::: "memory")
; #define PG8_BAR __builtin_amdgcn_s_barrier()
; #define PG8_SCHED __builtin_amdgcn_sched_barrier(0)
; template <class Epi, class Sched, bool ALIGN_EPI = false, bool SP2 = false>
; __device__ __forceinline__ void gemm_phase(PG8_LAS unsigned char* lds, const Gemm g, const Sched& S, const Epi& E) {
;     ...
;             PG8_LDA(At, 0, 1); PG8_STAGE(PG8_SB(0, 0), b2, voffB); PG8_STAGE(PG8_SB(0, 1), b2 + hstepB, voffB); PG8_STAGE(PG8_SA(0, 0), a2, voffA);
;             PG8_WAIT_V(8); PG8_WAIT_L(0); PG8_BAR; PG8_MMA(1, 0, At, B0); PG8_MMA(1, 1, At, B1); PG8_BAR; PG8_SCHED;
;             PG8_LDB(B0, 1, 0); PG8_LDB(B1, 1, 1); PG8_SCHED; PG8_LDA(At, 1, 0); PG8_STAGE(PG8_SA(0, 1), a2 + hstepA, voffA);
;             PG8_WAIT_V(8); PG8_WAIT_L(0); PG8_BAR; PG8_MMA(0, 0, At, B0); PG8_MMA(0, 1, At, B1); PG8_BAR; PG8_SCHED;
	s_setprio 1
	s_waitcnt lgkmcnt(0)
	v_mfma_f32_16x16x32_bf16 v[62:65], v[136:139], v[174:177], v[62:65]
	v_mfma_f32_16x16x32_bf16 v[58:61], v[150:153], v[174:177], v[58:61]
	v_mfma_f32_16x16x32_bf16 v[46:49], v[136:139], v[182:185], v[46:49]
	v_mfma_f32_16x16x32_bf16 v[42:45], v[150:153], v[182:185], v[42:45]
	v_mfma_f32_16x16x32_bf16 v[30:33], v[136:139], v[190:193], v[30:33]
	v_mfma_f32_16x16x32_bf16 v[26:29], v[150:153], v[190:193], v[26:29]
	s_mov_b32 m0, s63
	v_mfma_f32_16x16x32_bf16 v[14:17], v[136:139], v[222:225], v[14:17]
	global_load_lds_dwordx4 v[214:215], off
	v_mfma_f32_16x16x32_bf16 v[10:13], v[150:153], v[222:225], v[10:13]
	v_mfma_f32_16x16x32_bf16 v[62:65], v[140:143], v[178:181], v[62:65]
	v_mfma_f32_16x16x32_bf16 v[58:61], v[154:157], v[178:181], v[58:61]
	v_mfma_f32_16x16x32_bf16 v[46:49], v[140:143], v[186:189], v[46:49]
	v_mfma_f32_16x16x32_bf16 v[42:45], v[154:157], v[186:189], v[42:45]
	v_mfma_f32_16x16x32_bf16 v[30:33], v[140:143], v[210:213], v[30:33]
	v_mfma_f32_16x16x32_bf16 v[26:29], v[154:157], v[210:213], v[26:29]
	s_mov_b32 m0, s65
	v_mfma_f32_16x16x32_bf16 v[14:17], v[140:143], v[228:231], v[14:17]
	global_load_lds_dwordx4 v[232:233], off
	v_mfma_f32_16x16x32_bf16 v[10:13], v[154:157], v[228:231], v[10:13]
	s_setprio 0
	s_setprio 1
	v_mfma_f32_16x16x32_bf16 v[54:57], v[158:161], v[174:177], v[54:57]
	v_mfma_f32_16x16x32_bf16 v[50:53], v[166:169], v[174:177], v[50:53]
	v_mfma_f32_16x16x32_bf16 v[38:41], v[158:161], v[182:185], v[38:41]
	v_mfma_f32_16x16x32_bf16 v[34:37], v[166:169], v[182:185], v[34:37]
	v_mfma_f32_16x16x32_bf16 v[22:25], v[158:161], v[190:193], v[22:25]
	v_mfma_f32_16x16x32_bf16 v[18:21], v[166:169], v[190:193], v[18:21]
	v_mfma_f32_16x16x32_bf16 v[6:9], v[158:161], v[222:225], v[6:9]
	v_mfma_f32_16x16x32_bf16 v[2:5], v[166:169], v[222:225], v[2:5]
	v_mfma_f32_16x16x32_bf16 v[54:57], v[162:165], v[178:181], v[54:57]
	v_mfma_f32_16x16x32_bf16 v[50:53], v[170:173], v[178:181], v[50:53]
	v_mfma_f32_16x16x32_bf16 v[38:41], v[162:165], v[186:189], v[38:41]
	v_mfma_f32_16x16x32_bf16 v[34:37], v[170:173], v[186:189], v[34:37]
	v_mfma_f32_16x16x32_bf16 v[22:25], v[162:165], v[210:213], v[22:25]
	v_mfma_f32_16x16x32_bf16 v[18:21], v[170:173], v[210:213], v[18:21]
	v_mfma_f32_16x16x32_bf16 v[6:9], v[162:165], v[228:231], v[6:9]
	v_mfma_f32_16x16x32_bf16 v[2:5], v[170:173], v[228:231], v[2:5]
	s_setprio 0
	s_barrier
	s_add_i32 s2, s87, 0x100
	s_add_i32 s33, s69, 0x100
	v_add_u32_e32 v154, s2, v147
	v_add_u32_e32 v170, s33, v147
	ds_read_b128 v[136:139], v154
	ds_read_b128 v[140:143], v154 offset:1024
	ds_read_b128 v[150:153], v154 offset:2048
	ds_read_b128 v[154:157], v154 offset:3072
	ds_read_b128 v[158:161], v170
	ds_read_b128 v[162:165], v170 offset:1024
	ds_read_b128 v[166:169], v170 offset:2048
	ds_read_b128 v[170:173], v170 offset:3072
	s_add_u32 s60, s60, 0x200000
	s_addc_u32 s61, s61, 0
	s_mov_b32 m0, s72
	v_lshl_add_u64 v[234:235], s[60:61], 0, v[0:1]
	ds_read_b128 v[174:177], v149 offset:32768
	ds_read_b128 v[178:181], v149 offset:33792
	ds_read_b128 v[182:185], v149 offset:34816
	ds_read_b128 v[186:189], v149 offset:35840
	ds_read_b128 v[190:193], v149 offset:36864
	ds_read_b128 v[210:213], v149 offset:37888
	ds_read_b128 v[222:225], v149 offset:38912
	ds_read_b128 v[228:231], v149 offset:39936
	global_load_lds_dwordx4 v[234:235], off
	v_lshl_add_u64 v[234:235], s[60:61], 0, v[130:131]
	s_mov_b32 m0, s73
	s_nop 0
	global_load_lds_dwordx4 v[234:235], off
	s_waitcnt vmcnt(8)
	s_waitcnt lgkmcnt(0)
	s_barrier
	s_setprio 1
	s_waitcnt lgkmcnt(0)
	v_mfma_f32_16x16x32_bf16 v[126:129], v[136:139], v[174:177], v[126:129]
	v_mfma_f32_16x16x32_bf16 v[122:125], v[150:153], v[174:177], v[122:125]
	v_mfma_f32_16x16x32_bf16 v[110:113], v[136:139], v[182:185], v[110:113]
	v_mfma_f32_16x16x32_bf16 v[106:109], v[150:153], v[182:185], v[106:109]
	v_mfma_f32_16x16x32_bf16 v[94:97], v[136:139], v[190:193], v[94:97]
	v_mfma_f32_16x16x32_bf16 v[90:93], v[150:153], v[190:193], v[90:93]
	v_mfma_f32_16x16x32_bf16 v[78:81], v[136:139], v[222:225], v[78:81]
	v_mfma_f32_16x16x32_bf16 v[74:77], v[150:153], v[222:225], v[74:77]
	v_mfma_f32_16x16x32_bf16 v[126:129], v[140:143], v[178:181], v[126:129]
	v_mfma_f32_16x16x32_bf16 v[122:125], v[154:157], v[178:181], v[122:125]
	v_mfma_f32_16x16x32_bf16 v[110:113], v[140:143], v[186:189], v[110:113]
	v_mfma_f32_16x16x32_bf16 v[106:109], v[154:157], v[186:189], v[106:109]
	v_mfma_f32_16x16x32_bf16 v[94:97], v[140:143], v[210:213], v[94:97]
	v_mfma_f32_16x16x32_bf16 v[90:93], v[154:157], v[210:213], v[90:93]
	v_mfma_f32_16x16x32_bf16 v[78:81], v[140:143], v[228:231], v[78:81]
	v_mfma_f32_16x16x32_bf16 v[74:77], v[154:157], v[228:231], v[74:77]
	s_setprio 0
	s_setprio 1
	v_mfma_f32_16x16x32_bf16 v[118:121], v[158:161], v[174:177], v[118:121]
	v_mfma_f32_16x16x32_bf16 v[114:117], v[166:169], v[174:177], v[114:117]
	v_mfma_f32_16x16x32_bf16 v[102:105], v[158:161], v[182:185], v[102:105]
	v_mfma_f32_16x16x32_bf16 v[98:101], v[166:169], v[182:185], v[98:101]
	v_mfma_f32_16x16x32_bf16 v[86:89], v[158:161], v[190:193], v[86:89]
	v_mfma_f32_16x16x32_bf16 v[82:85], v[166:169], v[190:193], v[82:85]
	v_mfma_f32_16x16x32_bf16 v[70:73], v[158:161], v[222:225], v[70:73]
	v_mfma_f32_16x16x32_bf16 v[66:69], v[166:169], v[222:225], v[66:69]
	v_mfma_f32_16x16x32_bf16 v[118:121], v[162:165], v[178:181], v[118:121]
	v_mfma_f32_16x16x32_bf16 v[114:117], v[170:173], v[178:181], v[114:117]
	v_mfma_f32_16x16x32_bf16 v[102:105], v[162:165], v[186:189], v[102:105]
	v_mfma_f32_16x16x32_bf16 v[98:101], v[170:173], v[186:189], v[98:101]
	v_mfma_f32_16x16x32_bf16 v[86:89], v[162:165], v[210:213], v[86:89]
	v_mfma_f32_16x16x32_bf16 v[82:85], v[170:173], v[210:213], v[82:85]
	v_mfma_f32_16x16x32_bf16 v[70:73], v[162:165], v[228:231], v[70:73]
	v_mfma_f32_16x16x32_bf16 v[66:69], v[170:173], v[228:231], v[66:69]
	s_setprio 0
	s_barrier
; #define PG8_STAGE(bufoff, gbase, voff) do { _Pragma("unroll") for (int _i = 0; _i < 2; ++_i) \
;         __builtin_amdgcn_global_load_lds((const unsigned*)((const char*)(gbase) + (voff)[_i]), (PG8_LAS unsigned*)(lds + (bufoff) + ldsw + _i * 8192), 16, 0, 0); } while (0)
; #define PG8_LDA(dst, b, h) do { _Pragma("unroll") for (int m = 0; m < 4; ++m) _Pragma("unroll") for (int k = 0; k < 2; ++k) dst[m][k] = *(const PG8_LAS bf16x8*)(lds + PG8_SA(b, h) + aoff + m * 2048 + k * 1024); } while (0)
; #define PG8_MMA(ai, bj, At, Bt) do { __builtin_amdgcn_s_setprio(1); _Pragma("unroll") for (int m = 0; m < 4; ++m) _Pragma("unroll") for (int n = 0; n < 2; ++n) _Pragma("unroll") for (int k = 0; k < 2; ++k) \
;         acc[ai][bj][m][n] = __builtin_amdgcn_mfma_f32_16x16x32_bf16(Bt[n][k], At[m][k], acc[ai][bj][m][n], 0, 0, 0); __builtin_amdgcn_s_setprio(0); } while (0)
; #define PG8_WAIT_V(n) asm volatile("s_waitcnt vmcnt(" #n ")" ::: "memory")
; #define PG8_WAIT_L(n) asm volatile("s_waitcnt lgkmcnt(" #n ")" ::: "memory")
; #define PG8_BAR __builtin_amdgcn_s_barrier()
; #define PG8_SCHED __builtin_amdgcn_sched_barrier(0)
; template <class Epi, class Sched, bool ALIGN_EPI = false, bool SP2 = false>
; __device__ __forceinline__ void gemm_phase(PG8_LAS unsigned char* lds, const Gemm g, const Sched& S, const Epi& E) {
;     ...
;             PG8_WAIT_V(8); PG8_WAIT_L(0); PG8_BAR; PG8_MMA(0, 0, At, B0); PG8_MMA(0, 1, At, B1); PG8_BAR; PG8_SCHED;
;             PG8_LDA(At, 1, 1); PG8_STAGE(PG8_SB(1, 0), b3, voffB); PG8_STAGE(PG8_SB(1, 1), b3 + hstepB, voffB); PG8_STAGE(PG8_SA(1, 0), a3, voffA);
;             PG8_WAIT_V(8); PG8_WAIT_L(0); PG8_BAR; PG8_MMA(1, 0, At, B0); PG8_MMA(1, 1, At, B1); PG8_BAR; PG8_SCHED;
	s_add_i32 s2, s2, s36
	v_lshl_add_u64 v[144:145], v[144:145], 0, s[94:95]
	s_mov_b32 m0, s2
	ds_read_b128 v[174:177], v149 offset:49152
	ds_read_b128 v[178:181], v149 offset:50176
	ds_read_b128 v[182:185], v149 offset:51200
	ds_read_b128 v[186:189], v149 offset:52224
	ds_read_b128 v[190:193], v149 offset:53248
	ds_read_b128 v[210:213], v149 offset:54272
	ds_read_b128 v[222:225], v149 offset:55296
	ds_read_b128 v[228:231], v149 offset:56320
	global_load_lds_dwordx4 v[144:145], off
	s_add_i32 m0, s2, 0x2000
	s_add_u32 s10, s10, 0x200080
	v_lshl_add_u64 v[144:145], v[194:195], 0, s[94:95]
	s_addc_u32 s11, s11, 0
	s_add_i32 s2, s33, s36
	global_load_lds_dwordx4 v[144:145], off
	v_lshl_add_u64 v[144:145], s[10:11], 0, v[0:1]
	s_mov_b32 m0, s2
	s_nop 0
	global_load_lds_dwordx4 v[144:145], off
	v_lshl_add_u64 v[144:145], s[10:11], 0, v[130:131]
	s_add_i32 m0, s2, 0x2000
	s_nop 0
	global_load_lds_dwordx4 v[144:145], off
	v_lshl_add_u64 v[144:145], v[214:215], 0, s[94:95]
	s_waitcnt vmcnt(6)
	s_waitcnt lgkmcnt(0)
	s_barrier
	s_setprio 1
	s_waitcnt lgkmcnt(0)
	v_mfma_f32_16x16x32_bf16 v[62:65], v[136:139], v[174:177], v[62:65]
	v_mfma_f32_16x16x32_bf16 v[58:61], v[150:153], v[174:177], v[58:61]
	v_mfma_f32_16x16x32_bf16 v[46:49], v[136:139], v[182:185], v[46:49]
	v_mfma_f32_16x16x32_bf16 v[42:45], v[150:153], v[182:185], v[42:45]
	v_mfma_f32_16x16x32_bf16 v[30:33], v[136:139], v[190:193], v[30:33]
	v_mfma_f32_16x16x32_bf16 v[26:29], v[150:153], v[190:193], v[26:29]
	s_mov_b32 m0, s76
	v_mfma_f32_16x16x32_bf16 v[14:17], v[136:139], v[222:225], v[14:17]
	global_load_lds_dwordx4 v[144:145], off
	v_lshl_add_u64 v[144:145], v[232:233], 0, s[94:95]
	v_mfma_f32_16x16x32_bf16 v[10:13], v[150:153], v[222:225], v[10:13]
	v_mfma_f32_16x16x32_bf16 v[62:65], v[140:143], v[178:181], v[62:65]
	v_mfma_f32_16x16x32_bf16 v[58:61], v[154:157], v[178:181], v[58:61]
	v_mfma_f32_16x16x32_bf16 v[46:49], v[140:143], v[186:189], v[46:49]
	v_mfma_f32_16x16x32_bf16 v[42:45], v[154:157], v[186:189], v[42:45]
	v_mfma_f32_16x16x32_bf16 v[30:33], v[140:143], v[210:213], v[30:33]
	v_mfma_f32_16x16x32_bf16 v[26:29], v[154:157], v[210:213], v[26:29]
	s_mov_b32 m0, s77
	v_mfma_f32_16x16x32_bf16 v[14:17], v[140:143], v[228:231], v[14:17]
	global_load_lds_dwordx4 v[144:145], off
	v_mfma_f32_16x16x32_bf16 v[10:13], v[154:157], v[228:231], v[10:13]
	s_setprio 0
	s_setprio 1
	v_mfma_f32_16x16x32_bf16 v[54:57], v[158:161], v[174:177], v[54:57]
	v_mfma_f32_16x16x32_bf16 v[50:53], v[166:169], v[174:177], v[50:53]
	v_mfma_f32_16x16x32_bf16 v[38:41], v[158:161], v[182:185], v[38:41]
	v_mfma_f32_16x16x32_bf16 v[34:37], v[166:169], v[182:185], v[34:37]
	v_mfma_f32_16x16x32_bf16 v[22:25], v[158:161], v[190:193], v[22:25]
	v_mfma_f32_16x16x32_bf16 v[18:21], v[166:169], v[190:193], v[18:21]
	v_mfma_f32_16x16x32_bf16 v[6:9], v[158:161], v[222:225], v[6:9]
	v_mfma_f32_16x16x32_bf16 v[2:5], v[166:169], v[222:225], v[2:5]
	v_mfma_f32_16x16x32_bf16 v[54:57], v[162:165], v[178:181], v[54:57]
	v_mfma_f32_16x16x32_bf16 v[50:53], v[170:173], v[178:181], v[50:53]
	v_mfma_f32_16x16x32_bf16 v[38:41], v[162:165], v[186:189], v[38:41]
	v_mfma_f32_16x16x32_bf16 v[34:37], v[170:173], v[186:189], v[34:37]
	v_mfma_f32_16x16x32_bf16 v[22:25], v[162:165], v[210:213], v[22:25]
	v_mfma_f32_16x16x32_bf16 v[18:21], v[170:173], v[210:213], v[18:21]
	v_mfma_f32_16x16x32_bf16 v[6:9], v[162:165], v[228:231], v[6:9]
	v_mfma_f32_16x16x32_bf16 v[2:5], v[170:173], v[228:231], v[2:5]
	s_setprio 0
	s_barrier
	s_add_i32 vcc_lo, vcc_lo, 2
	s_add_u32 s8, s8, 0x100
	s_addc_u32 s9, s9, 0
	s_add_u32 s91, s91, 0x100
	s_addc_u32 s93, s93, 0
	s_cmpk_gt_u32 vcc_lo, 0x7d
	s_cbranch_scc0 .LBB0_297
	s_and_b64 vcc, exec, s[42:43]
	s_cbranch_vccz .LBB0_300
	s_barrier

; #define PG8_STAGE(bufoff, gbase, voff) do { _Pragma("unroll") for (int _i = 0; _i < 2; ++_i) \
;         __builtin_amdgcn_global_load_lds((const unsigned*)((const char*)(gbase) + (voff)[_i]), (PG8_LAS unsigned*)(lds + (bufoff) + ldsw + _i * 8192), 16, 0, 0); } while (0)
; #define PG8_LDA(dst, b, h) do { _Pragma("unroll") for (int m = 0; m < 4; ++m) _Pragma("unroll") for (int k = 0; k < 2; ++k) dst[m][k] = *(const PG8_LAS bf16x8*)(lds + PG8_SA(b, h) + aoff + m * 2048 + k * 1024); } while (0)
; #define PG8_LDB(dst, b, h) do { _Pragma("unroll") for (int n = 0; n < 2; ++n) _Pragma("unroll") for (int k = 0; k < 2; ++k) dst[n][k] = *(const PG8_LAS bf16x8*)(lds + PG8_SB(b, h) + boff + n * 2048 + k * 1024); } while (0)
; #define PG8_MMA(ai, bj, At, Bt) do { __builtin_amdgcn_s_setprio(1); _Pragma("unroll") for (int m = 0; m < 4; ++m) _Pragma("unroll") for (int n = 0; n < 2; ++n) _Pragma("unroll") for (int k = 0; k < 2; ++k) \
;         acc[ai][bj][m][n] = __builtin_amdgcn_mfma_f32_16x16x32_bf16(Bt[n][k], At[m][k], acc[ai][bj][m][n], 0, 0, 0); __builtin_amdgcn_s_setprio(0); } while (0)
; #define PG8_WAIT_V(n) asm volatile("s_waitcnt vmcnt(" #n ")" ::: "memory")
; #define PG8_WAIT_L(n) asm volatile("s_waitcnt lgkmcnt(" #n ")" ::: "memory")
; #define PG8_BAR __builtin_amdgcn_s_barrier()
; #define PG8_SCHED __builtin_amdgcn_sched_barrier(0)
; template <class Epi, class Sched, bool ALIGN_EPI = false, bool SP2 = false>
; __device__ __forceinline__ void gemm_phase(PG8_LAS unsigned char* lds, const Gemm g, const Sched& S, const Epi& E) {
;     ...
;             const bool last = (t == nt - 2);
;             const char* a1 = cA + (size_t)(t + 1) * kstep;
;             const char* a2 = last ? nA : cA + (size_t)(t + 2) * kstep; const char* b2 = last ? nB : cB + (size_t)(t + 2) * kstep;
;             const char* a3 = a2 + kstep; const char* b3 = b2 + kstep;
;             if (last && has_next) S.a_ready(nxt);
;             if constexpr (SP2) {
;             PG8_LDB(B0, 0, 0); PG8_LDB(B1, 0, 1); PG8_SCHED; PG8_LDA(At, 0, 0); PG8_STAGE(PG8_SA(1, 1), a1 + hstepA, voffA);
;             PG8_WAIT_V(8); PG8_WAIT_L(0); PG8_BAR; PG8_MMA(0, 0, At, B0); PG8_MMA(0, 1, At, B1); PG8_BAR; PG8_SCHED;
;             PG8_LDA(At, 0, 1); PG8_STAGE(PG8_SB(0, 0), b2, voffB); PG8_STAGE(PG8_SB(0, 1), b2 + hstepB, voffB); PG8_STAGE(PG8_SA(0, 0), a2, voffA);
.LBB0_415:
	s_add_u32 s2, s6, 0xfff80080
	s_addc_u32 s33, s7, -1
	s_add_i32 s68, s17, 0x100
	s_cmp_eq_u32 s72, 28
	s_cselect_b32 s47, s39, s33
	s_cselect_b32 s46, s62, s2
	v_add_u32_e32 v144, s68, v147
	s_cselect_b32 s45, s27, s70
	s_cselect_b32 s44, s63, s65
	s_add_i32 s2, s24, 0x100
	ds_read_b128 v[140:143], v144
	ds_read_b128 v[150:153], v144 offset:1024
	ds_read_b128 v[154:157], v144 offset:2048
	ds_read_b128 v[158:161], v144 offset:3072
	v_add_u32_e32 v144, s2, v147
	ds_read_b128 v[162:165], v144
	ds_read_b128 v[166:169], v144 offset:1024
	ds_read_b128 v[170:173], v144 offset:2048
	ds_read_b128 v[174:177], v144 offset:3072
	v_lshl_add_u64 v[194:195], s[6:7], 0, v[136:137]
	s_add_i32 m0, s50, 0xc000
	ds_read_b128 v[178:181], v149
	ds_read_b128 v[182:185], v149 offset:1024
	ds_read_b128 v[186:189], v149 offset:2048
	ds_read_b128 v[190:193], v149 offset:3072
	ds_read_b128 v[210:213], v149 offset:4096
	ds_read_b128 v[222:225], v149 offset:5120
	ds_read_b128 v[228:231], v149 offset:6144
	ds_read_b128 v[232:235], v149 offset:7168
	global_load_lds_dwordx4 v[194:195], off
	v_lshl_add_u64 v[194:195], s[6:7], 0, v[138:139]
	s_add_i32 m0, s50, 0xe000
	s_nop 0
	global_load_lds_dwordx4 v[194:195], off
	s_waitcnt vmcnt(8)
	s_waitcnt lgkmcnt(0)
	s_barrier
	s_setprio 1
	s_waitcnt lgkmcnt(0)
	v_mfma_f32_16x16x32_bf16 v[126:129], v[140:143], v[178:181], v[126:129]
	v_mfma_f32_16x16x32_bf16 v[122:125], v[154:157], v[178:181], v[122:125]
	v_mfma_f32_16x16x32_bf16 v[110:113], v[140:143], v[186:189], v[110:113]
	v_mfma_f32_16x16x32_bf16 v[106:109], v[154:157], v[186:189], v[106:109]
	v_mfma_f32_16x16x32_bf16 v[94:97], v[140:143], v[210:213], v[94:97]
	v_mfma_f32_16x16x32_bf16 v[90:93], v[154:157], v[210:213], v[90:93]
	v_mfma_f32_16x16x32_bf16 v[78:81], v[140:143], v[228:231], v[78:81]
	v_mfma_f32_16x16x32_bf16 v[74:77], v[154:157], v[228:231], v[74:77]
	v_mfma_f32_16x16x32_bf16 v[126:129], v[150:153], v[182:185], v[126:129]
	v_mfma_f32_16x16x32_bf16 v[122:125], v[158:161], v[182:185], v[122:125]
	v_mfma_f32_16x16x32_bf16 v[110:113], v[150:153], v[190:193], v[110:113]
	v_mfma_f32_16x16x32_bf16 v[106:109], v[158:161], v[190:193], v[106:109]
	v_mfma_f32_16x16x32_bf16 v[94:97], v[150:153], v[222:225], v[94:97]
	v_mfma_f32_16x16x32_bf16 v[90:93], v[158:161], v[222:225], v[90:93]
	v_mfma_f32_16x16x32_bf16 v[78:81], v[150:153], v[232:235], v[78:81]
	v_mfma_f32_16x16x32_bf16 v[74:77], v[158:161], v[232:235], v[74:77]
	s_setprio 0
	s_setprio 1
	v_mfma_f32_16x16x32_bf16 v[118:121], v[162:165], v[178:181], v[118:121]
	v_mfma_f32_16x16x32_bf16 v[114:117], v[170:173], v[178:181], v[114:117]
	v_mfma_f32_16x16x32_bf16 v[102:105], v[162:165], v[186:189], v[102:105]
	v_mfma_f32_16x16x32_bf16 v[98:101], v[170:173], v[186:189], v[98:101]
	v_mfma_f32_16x16x32_bf16 v[86:89], v[162:165], v[210:213], v[86:89]
	v_mfma_f32_16x16x32_bf16 v[82:85], v[170:173], v[210:213], v[82:85]
	v_mfma_f32_16x16x32_bf16 v[70:73], v[162:165], v[228:231], v[70:73]
	v_mfma_f32_16x16x32_bf16 v[66:69], v[170:173], v[228:231], v[66:69]
	v_mfma_f32_16x16x32_bf16 v[118:121], v[166:169], v[182:185], v[118:121]
	v_mfma_f32_16x16x32_bf16 v[114:117], v[174:177], v[182:185], v[114:117]
	v_mfma_f32_16x16x32_bf16 v[102:105], v[166:169], v[190:193], v[102:105]
	v_mfma_f32_16x16x32_bf16 v[98:101], v[174:177], v[190:193], v[98:101]
	v_mfma_f32_16x16x32_bf16 v[86:89], v[166:169], v[222:225], v[86:89]
	v_mfma_f32_16x16x32_bf16 v[82:85], v[174:177], v[222:225], v[82:85]
	v_mfma_f32_16x16x32_bf16 v[70:73], v[166:169], v[232:235], v[70:73]
	v_mfma_f32_16x16x32_bf16 v[66:69], v[174:177], v[232:235], v[66:69]
	s_setprio 0
	s_barrier
	s_add_i32 s33, s68, s49
	v_lshl_add_u64 v[194:195], s[44:45], 0, v[0:1]
	s_mov_b32 m0, s33
	ds_read_b128 v[178:181], v149 offset:16384
	ds_read_b128 v[182:185], v149 offset:17408
	ds_read_b128 v[186:189], v149 offset:18432
	ds_read_b128 v[190:193], v149 offset:19456
	ds_read_b128 v[210:213], v149 offset:20480
	ds_read_b128 v[222:225], v149 offset:21504
	ds_read_b128 v[228:231], v149 offset:22528
	ds_read_b128 v[232:235], v149 offset:23552
	global_load_lds_dwordx4 v[194:195], off
	s_add_i32 m0, s33, 0x2000
	s_add_u32 s76, s44, 0x80000
	v_lshl_add_u64 v[214:215], s[44:45], 0, v[130:131]
	s_addc_u32 s77, s45, 0
	s_add_i32 s2, s2, s49
	global_load_lds_dwordx4 v[214:215], off
	v_lshl_add_u64 v[236:237], s[76:77], 0, v[0:1]
	s_mov_b32 m0, s2
	v_lshl_add_u64 v[238:239], s[46:47], 0, v[132:133]
	global_load_lds_dwordx4 v[236:237], off
	v_lshl_add_u64 v[236:237], s[76:77], 0, v[130:131]
	s_add_i32 m0, s2, 0x2000
	s_nop 0
	global_load_lds_dwordx4 v[236:237], off
	v_lshl_add_u64 v[236:237], s[46:47], 0, v[134:135]
	s_waitcnt vmcnt(6)
	s_waitcnt lgkmcnt(0)
	s_barrier
; #define PG8_STAGE(bufoff, gbase, voff) do { _Pragma("unroll") for (int _i = 0; _i < 2; ++_i) \
;         __builtin_amdgcn_global_load_lds((const unsigned*)((const char*)(gbase) + (voff)[_i]), (PG8_LAS unsigned*)(lds + (bufoff) + ldsw + _i * 8192), 16, 0, 0); } while (0)
; #define PG8_LDA(dst, b, h) do { _Pragma("unroll") for (int m = 0; m < 4; ++m) _Pragma("unroll") for (int k = 0; k < 2; ++k) dst[m][k] = *(const PG8_LAS bf16x8*)(lds + PG8_SA(b, h) + aoff + m * 2048 + k * 1024); } while (0)
; #define PG8_LDB(dst, b, h) do { _Pragma("unroll") for (int n = 0; n < 2; ++n) _Pragma("unroll") for (int k = 0; k < 2; ++k) dst[n][k] = *(const PG8_LAS bf16x8*)(lds + PG8_SB(b, h) + boff + n * 2048 + k * 1024); } while (0)
; #define PG8_MMA(ai, bj, At, Bt) do { __builtin_amdgcn_s_setprio(1); _Pragma("unroll") for (int m = 0; m < 4; ++m) _Pragma("unroll") for (int n = 0; n < 2; ++n) _Pragma("unroll") for (int k = 0; k < 2; ++k) \
;         acc[ai][bj][m][n] = __builtin_amdgcn_mfma_f32_16x16x32_bf16(Bt[n][k], At[m][k], acc[ai][bj][m][n], 0, 0, 0); __builtin_amdgcn_s_setprio(0); } while (0)
; #define PG8_WAIT_V(n) asm volatile("s_waitcnt vmcnt(" #n ")" ::: "memory")
; #define PG8_WAIT_L(n) asm volatile("s_waitcnt lgkmcnt(" #n ")" ::: "memory")
; #define PG8_BAR __builtin_amdgcn_s_barrier()
; #define PG8_SCHED __builtin_amdgcn_sched_barrier(0)
; template <class Epi, class Sched, bool ALIGN_EPI = false, bool SP2 = false>
; __device__ __forceinline__ void gemm_phase(PG8_LAS unsigned char* lds, const Gemm g, const Sched& S, const Epi& E) {
;     ...
;             PG8_LDA(At, 0, 1); PG8_STAGE(PG8_SB(0, 0), b2, voffB); PG8_STAGE(PG8_SB(0, 1), b2 + hstepB, voffB); PG8_STAGE(PG8_SA(0, 0), a2, voffA);
;             PG8_WAIT_V(8); PG8_WAIT_L(0); PG8_BAR; PG8_MMA(1, 0, At, B0); PG8_MMA(1, 1, At, B1); PG8_BAR; PG8_SCHED;
;             PG8_LDB(B0, 1, 0); PG8_LDB(B1, 1, 1); PG8_SCHED; PG8_LDA(At, 1, 0); PG8_STAGE(PG8_SA(0, 1), a2 + hstepA, voffA);
;             PG8_WAIT_V(8); PG8_WAIT_L(0); PG8_BAR; PG8_MMA(0, 0, At, B0); PG8_MMA(0, 1, At, B1); PG8_BAR; PG8_SCHED;
	s_setprio 1
	s_waitcnt lgkmcnt(0)
	v_mfma_f32_16x16x32_bf16 v[62:65], v[140:143], v[178:181], v[62:65]
	v_mfma_f32_16x16x32_bf16 v[58:61], v[154:157], v[178:181], v[58:61]
	v_mfma_f32_16x16x32_bf16 v[46:49], v[140:143], v[186:189], v[46:49]
	v_mfma_f32_16x16x32_bf16 v[42:45], v[154:157], v[186:189], v[42:45]
	v_mfma_f32_16x16x32_bf16 v[30:33], v[140:143], v[210:213], v[30:33]
	v_mfma_f32_16x16x32_bf16 v[26:29], v[154:157], v[210:213], v[26:29]
	s_mov_b32 m0, s50
	v_mfma_f32_16x16x32_bf16 v[14:17], v[140:143], v[228:231], v[14:17]
	global_load_lds_dwordx4 v[236:237], off
	v_mfma_f32_16x16x32_bf16 v[10:13], v[154:157], v[228:231], v[10:13]
	v_mfma_f32_16x16x32_bf16 v[62:65], v[150:153], v[182:185], v[62:65]
	v_mfma_f32_16x16x32_bf16 v[58:61], v[158:161], v[182:185], v[58:61]
	v_mfma_f32_16x16x32_bf16 v[46:49], v[150:153], v[190:193], v[46:49]
	v_mfma_f32_16x16x32_bf16 v[42:45], v[158:161], v[190:193], v[42:45]
	v_mfma_f32_16x16x32_bf16 v[30:33], v[150:153], v[222:225], v[30:33]
	v_mfma_f32_16x16x32_bf16 v[26:29], v[158:161], v[222:225], v[26:29]
	s_mov_b32 m0, s51
	v_mfma_f32_16x16x32_bf16 v[14:17], v[150:153], v[232:235], v[14:17]
	global_load_lds_dwordx4 v[238:239], off
	v_mfma_f32_16x16x32_bf16 v[10:13], v[158:161], v[232:235], v[10:13]
	s_setprio 0
	s_setprio 1
	v_mfma_f32_16x16x32_bf16 v[54:57], v[162:165], v[178:181], v[54:57]
	v_mfma_f32_16x16x32_bf16 v[50:53], v[170:173], v[178:181], v[50:53]
	v_mfma_f32_16x16x32_bf16 v[38:41], v[162:165], v[186:189], v[38:41]
	v_mfma_f32_16x16x32_bf16 v[34:37], v[170:173], v[186:189], v[34:37]
	v_mfma_f32_16x16x32_bf16 v[22:25], v[162:165], v[210:213], v[22:25]
	v_mfma_f32_16x16x32_bf16 v[18:21], v[170:173], v[210:213], v[18:21]
	v_mfma_f32_16x16x32_bf16 v[6:9], v[162:165], v[228:231], v[6:9]
	v_mfma_f32_16x16x32_bf16 v[2:5], v[170:173], v[228:231], v[2:5]
	v_mfma_f32_16x16x32_bf16 v[54:57], v[166:169], v[182:185], v[54:57]
	v_mfma_f32_16x16x32_bf16 v[50:53], v[174:177], v[182:185], v[50:53]
	v_mfma_f32_16x16x32_bf16 v[38:41], v[166:169], v[190:193], v[38:41]
	v_mfma_f32_16x16x32_bf16 v[34:37], v[174:177], v[190:193], v[34:37]
	v_mfma_f32_16x16x32_bf16 v[22:25], v[166:169], v[222:225], v[22:25]
	v_mfma_f32_16x16x32_bf16 v[18:21], v[174:177], v[222:225], v[18:21]
	v_mfma_f32_16x16x32_bf16 v[6:9], v[166:169], v[232:235], v[6:9]
	v_mfma_f32_16x16x32_bf16 v[2:5], v[174:177], v[232:235], v[2:5]
	s_setprio 0
	s_barrier
	s_add_i32 s2, s87, 0x100
	v_add_u32_e32 v144, s2, v147
	s_add_i32 s33, s69, 0x100
	ds_read_b128 v[140:143], v144
	ds_read_b128 v[150:153], v144 offset:1024
	ds_read_b128 v[154:157], v144 offset:2048
	ds_read_b128 v[158:161], v144 offset:3072
	v_add_u32_e32 v144, s33, v147
	ds_read_b128 v[162:165], v144
	ds_read_b128 v[166:169], v144 offset:1024
	ds_read_b128 v[170:173], v144 offset:2048
	ds_read_b128 v[174:177], v144 offset:3072
	s_add_u32 s46, s46, 0x80000
	s_addc_u32 s47, s47, 0
	s_mov_b32 m0, s57
	v_lshl_add_u64 v[240:241], s[46:47], 0, v[134:135]
	ds_read_b128 v[178:181], v149 offset:32768
	ds_read_b128 v[182:185], v149 offset:33792
	ds_read_b128 v[186:189], v149 offset:34816
	ds_read_b128 v[190:193], v149 offset:35840
	ds_read_b128 v[210:213], v149 offset:36864
	ds_read_b128 v[222:225], v149 offset:37888
	ds_read_b128 v[228:231], v149 offset:38912
	ds_read_b128 v[232:235], v149 offset:39936
	global_load_lds_dwordx4 v[240:241], off
	v_lshl_add_u64 v[240:241], s[46:47], 0, v[132:133]
	s_mov_b32 m0, s58
	s_nop 0
	global_load_lds_dwordx4 v[240:241], off
	s_waitcnt vmcnt(8)
	s_waitcnt lgkmcnt(0)
	s_barrier
	s_setprio 1
	s_waitcnt lgkmcnt(0)
	v_mfma_f32_16x16x32_bf16 v[126:129], v[140:143], v[178:181], v[126:129]
	v_mfma_f32_16x16x32_bf16 v[122:125], v[154:157], v[178:181], v[122:125]
	v_mfma_f32_16x16x32_bf16 v[110:113], v[140:143], v[186:189], v[110:113]
	v_mfma_f32_16x16x32_bf16 v[106:109], v[154:157], v[186:189], v[106:109]
	v_mfma_f32_16x16x32_bf16 v[94:97], v[140:143], v[210:213], v[94:97]
	v_mfma_f32_16x16x32_bf16 v[90:93], v[154:157], v[210:213], v[90:93]
	v_mfma_f32_16x16x32_bf16 v[78:81], v[140:143], v[228:231], v[78:81]
	v_mfma_f32_16x16x32_bf16 v[74:77], v[154:157], v[228:231], v[74:77]
	v_mfma_f32_16x16x32_bf16 v[126:129], v[150:153], v[182:185], v[126:129]
	v_mfma_f32_16x16x32_bf16 v[122:125], v[158:161], v[182:185], v[122:125]
	v_mfma_f32_16x16x32_bf16 v[110:113], v[150:153], v[190:193], v[110:113]
	v_mfma_f32_16x16x32_bf16 v[106:109], v[158:161], v[190:193], v[106:109]
	v_mfma_f32_16x16x32_bf16 v[94:97], v[150:153], v[222:225], v[94:97]
	v_mfma_f32_16x16x32_bf16 v[90:93], v[158:161], v[222:225], v[90:93]
	v_mfma_f32_16x16x32_bf16 v[78:81], v[150:153], v[232:235], v[78:81]
	v_mfma_f32_16x16x32_bf16 v[74:77], v[158:161], v[232:235], v[74:77]
	s_setprio 0
	s_setprio 1
	v_mfma_f32_16x16x32_bf16 v[118:121], v[162:165], v[178:181], v[118:121]
	v_mfma_f32_16x16x32_bf16 v[114:117], v[170:173], v[178:181], v[114:117]
	v_mfma_f32_16x16x32_bf16 v[102:105], v[162:165], v[186:189], v[102:105]
	v_mfma_f32_16x16x32_bf16 v[98:101], v[170:173], v[186:189], v[98:101]
	v_mfma_f32_16x16x32_bf16 v[86:89], v[162:165], v[210:213], v[86:89]
	v_mfma_f32_16x16x32_bf16 v[82:85], v[170:173], v[210:213], v[82:85]
	v_mfma_f32_16x16x32_bf16 v[70:73], v[162:165], v[228:231], v[70:73]
	v_mfma_f32_16x16x32_bf16 v[66:69], v[170:173], v[228:231], v[66:69]
	v_mfma_f32_16x16x32_bf16 v[118:121], v[166:169], v[182:185], v[118:121]
	v_mfma_f32_16x16x32_bf16 v[114:117], v[174:177], v[182:185], v[114:117]
	v_mfma_f32_16x16x32_bf16 v[102:105], v[166:169], v[190:193], v[102:105]
	v_mfma_f32_16x16x32_bf16 v[98:101], v[174:177], v[190:193], v[98:101]
	v_mfma_f32_16x16x32_bf16 v[86:89], v[166:169], v[222:225], v[86:89]
	v_mfma_f32_16x16x32_bf16 v[82:85], v[174:177], v[222:225], v[82:85]
	v_mfma_f32_16x16x32_bf16 v[70:73], v[166:169], v[232:235], v[70:73]
	v_mfma_f32_16x16x32_bf16 v[66:69], v[174:177], v[232:235], v[66:69]
	s_setprio 0
	s_barrier
; #define PG8_STAGE(bufoff, gbase, voff) do { _Pragma("unroll") for (int _i = 0; _i < 2; ++_i) \
;         __builtin_amdgcn_global_load_lds((const unsigned*)((const char*)(gbase) + (voff)[_i]), (PG8_LAS unsigned*)(lds + (bufoff) + ldsw + _i * 8192), 16, 0, 0); } while (0)
; #define PG8_LDA(dst, b, h) do { _Pragma("unroll") for (int m = 0; m < 4; ++m) _Pragma("unroll") for (int k = 0; k < 2; ++k) dst[m][k] = *(const PG8_LAS bf16x8*)(lds + PG8_SA(b, h) + aoff + m * 2048 + k * 1024); } while (0)
; #define PG8_MMA(ai, bj, At, Bt) do { __builtin_amdgcn_s_setprio(1); _Pragma("unroll") for (int m = 0; m < 4; ++m) _Pragma("unroll") for (int n = 0; n < 2; ++n) _Pragma("unroll") for (int k = 0; k < 2; ++k) \
;         acc[ai][bj][m][n] = __builtin_amdgcn_mfma_f32_16x16x32_bf16(Bt[n][k], At[m][k], acc[ai][bj][m][n], 0, 0, 0); __builtin_amdgcn_s_setprio(0); } while (0)
; #define PG8_WAIT_V(n) asm volatile("s_waitcnt vmcnt(" #n ")" ::: "memory")
; #define PG8_WAIT_L(n) asm volatile("s_waitcnt lgkmcnt(" #n ")" ::: "memory")
; #define PG8_BAR __builtin_amdgcn_s_barrier()
; #define PG8_SCHED __builtin_amdgcn_sched_barrier(0)
; template <class Epi, class Sched, bool ALIGN_EPI = false, bool SP2 = false>
; __device__ __forceinline__ void gemm_phase(PG8_LAS unsigned char* lds, const Gemm g, const Sched& S, const Epi& E) {
;     ...
;             PG8_WAIT_V(8); PG8_WAIT_L(0); PG8_BAR; PG8_MMA(0, 0, At, B0); PG8_MMA(0, 1, At, B1); PG8_BAR; PG8_SCHED;
;             PG8_LDA(At, 1, 1); PG8_STAGE(PG8_SB(1, 0), b3, voffB); PG8_STAGE(PG8_SB(1, 1), b3 + hstepB, voffB); PG8_STAGE(PG8_SA(1, 0), a3, voffA);
;             PG8_WAIT_V(8); PG8_WAIT_L(0); PG8_BAR; PG8_MMA(1, 0, At, B0); PG8_MMA(1, 1, At, B1); PG8_BAR; PG8_SCHED;
	s_add_i32 s2, s2, s49
	v_lshl_add_u64 v[194:195], v[194:195], 0, s[94:95]
	s_mov_b32 m0, s2
	ds_read_b128 v[178:181], v149 offset:49152
	ds_read_b128 v[182:185], v149 offset:50176
	ds_read_b128 v[186:189], v149 offset:51200
	ds_read_b128 v[190:193], v149 offset:52224
	ds_read_b128 v[210:213], v149 offset:53248
	ds_read_b128 v[222:225], v149 offset:54272
	ds_read_b128 v[228:231], v149 offset:55296
	ds_read_b128 v[232:235], v149 offset:56320
	global_load_lds_dwordx4 v[194:195], off
	s_add_i32 m0, s2, 0x2000
	s_add_u32 s44, s44, 0x80080
	v_lshl_add_u64 v[194:195], v[214:215], 0, s[94:95]
	s_addc_u32 s45, s45, 0
	s_add_i32 s2, s33, s49
	global_load_lds_dwordx4 v[194:195], off
	v_lshl_add_u64 v[194:195], s[44:45], 0, v[0:1]
	s_mov_b32 m0, s2
	s_nop 0
	global_load_lds_dwordx4 v[194:195], off
	v_lshl_add_u64 v[194:195], s[44:45], 0, v[130:131]
	s_add_i32 m0, s2, 0x2000
	s_nop 0
	global_load_lds_dwordx4 v[194:195], off
	v_lshl_add_u64 v[194:195], v[236:237], 0, s[94:95]
	s_waitcnt vmcnt(6)
	s_waitcnt lgkmcnt(0)
	s_barrier
	s_setprio 1
	s_waitcnt lgkmcnt(0)
	v_mfma_f32_16x16x32_bf16 v[62:65], v[140:143], v[178:181], v[62:65]
	v_mfma_f32_16x16x32_bf16 v[58:61], v[154:157], v[178:181], v[58:61]
	v_mfma_f32_16x16x32_bf16 v[46:49], v[140:143], v[186:189], v[46:49]
	v_mfma_f32_16x16x32_bf16 v[42:45], v[154:157], v[186:189], v[42:45]
	v_mfma_f32_16x16x32_bf16 v[30:33], v[140:143], v[210:213], v[30:33]
	v_mfma_f32_16x16x32_bf16 v[26:29], v[154:157], v[210:213], v[26:29]
	s_mov_b32 m0, s59
	v_mfma_f32_16x16x32_bf16 v[14:17], v[140:143], v[228:231], v[14:17]
	global_load_lds_dwordx4 v[194:195], off
	v_lshl_add_u64 v[194:195], v[238:239], 0, s[94:95]
	v_mfma_f32_16x16x32_bf16 v[10:13], v[154:157], v[228:231], v[10:13]
	v_mfma_f32_16x16x32_bf16 v[62:65], v[150:153], v[182:185], v[62:65]
	v_mfma_f32_16x16x32_bf16 v[58:61], v[158:161], v[182:185], v[58:61]
	v_mfma_f32_16x16x32_bf16 v[46:49], v[150:153], v[190:193], v[46:49]
	v_mfma_f32_16x16x32_bf16 v[42:45], v[158:161], v[190:193], v[42:45]
	v_mfma_f32_16x16x32_bf16 v[30:33], v[150:153], v[222:225], v[30:33]
	v_mfma_f32_16x16x32_bf16 v[26:29], v[158:161], v[222:225], v[26:29]
	s_mov_b32 m0, s60
	v_mfma_f32_16x16x32_bf16 v[14:17], v[150:153], v[232:235], v[14:17]
	global_load_lds_dwordx4 v[194:195], off
	v_mfma_f32_16x16x32_bf16 v[10:13], v[158:161], v[232:235], v[10:13]
	s_setprio 0
	s_setprio 1
	v_mfma_f32_16x16x32_bf16 v[54:57], v[162:165], v[178:181], v[54:57]
	v_mfma_f32_16x16x32_bf16 v[50:53], v[170:173], v[178:181], v[50:53]
	v_mfma_f32_16x16x32_bf16 v[38:41], v[162:165], v[186:189], v[38:41]
	v_mfma_f32_16x16x32_bf16 v[34:37], v[170:173], v[186:189], v[34:37]
	v_mfma_f32_16x16x32_bf16 v[22:25], v[162:165], v[210:213], v[22:25]
	v_mfma_f32_16x16x32_bf16 v[18:21], v[170:173], v[210:213], v[18:21]
	v_mfma_f32_16x16x32_bf16 v[6:9], v[162:165], v[228:231], v[6:9]
	v_mfma_f32_16x16x32_bf16 v[2:5], v[170:173], v[228:231], v[2:5]
	v_mfma_f32_16x16x32_bf16 v[54:57], v[166:169], v[182:185], v[54:57]
	v_mfma_f32_16x16x32_bf16 v[50:53], v[174:177], v[182:185], v[50:53]
	v_mfma_f32_16x16x32_bf16 v[38:41], v[166:169], v[190:193], v[38:41]
	v_mfma_f32_16x16x32_bf16 v[34:37], v[174:177], v[190:193], v[34:37]
	v_mfma_f32_16x16x32_bf16 v[22:25], v[166:169], v[222:225], v[22:25]
	v_mfma_f32_16x16x32_bf16 v[18:21], v[174:177], v[222:225], v[18:21]
	v_mfma_f32_16x16x32_bf16 v[6:9], v[166:169], v[232:235], v[6:9]
	v_mfma_f32_16x16x32_bf16 v[2:5], v[174:177], v[232:235], v[2:5]
	s_setprio 0
	s_barrier
	s_add_i32 s72, s72, 2
	s_add_u32 s6, s6, 0x100
	s_addc_u32 s7, s7, 0
	s_add_u32 s65, s65, 0x100
	s_addc_u32 s70, s70, 0
	s_cmp_gt_u32 s72, 29
	s_cbranch_scc0 .LBB0_415
	s_and_b64 vcc, exec, s[14:15]
	s_cbranch_vccz .LBB0_418
	s_barrier
